# Infinity-Cache touch of the next layer's f32 weights from the FFN-up epilogues with default cache policy (no nt), on top of v47
# baseline (speedup 1.0000x reference)
; #define PG8_LAS __attribute__((address_space(3)))
; #define EPV_K(dst1, dst2) do { _Pragma("unroll") for (int bj = 0; bj < 2; ++bj) _Pragma("unroll") for (int n = 0; n < 2; ++n) { \
;         dst1[bj][n] = *(const PG8_LAS f32x4*)(ev + 2048 + (wc * 32 + 8 * fq + bj * HALF + 4 * n) * 4); dst2[bj][n] = *(const PG8_LAS f32x4*)(ev + 3072 + (wc * 32 + 8 * fq + bj * HALF + 4 * n) * 4); } } while (0)
;     __device__ __forceinline__ void operator()(const f32x4 (&acc)[2][2][4][2], const Unit& u, int wr, int wc, int fr, int fq, int rowmask, const PG8_LAS unsigned char* ev) const {
;         const int pn = u.pn, row0 = u.pm * BM + wr * 64 + fr, gcol0 = pn * BM + wc * 32 + 8 * fq, oc = pn * 128 + wc * 32 + 8 * fq;
;         f32x4 k1[2][2], k2[2][2]; EPV_K(k1, k2);
;         const int rl0 = wr * 64 + fr;
.Ltch_go:
	s_lshl_b32 s1, s1, 13
	s_add_u32 s84, s84, s1
	v_readlane_b32 s0, v250, 0
	v_readlane_b32 s1, v250, 1
	s_add_u32 s0, s0, s96
	s_addc_u32 s1, s1, 0
	s_load_dwordx2 s[0:1], s[0:1], 0x0
	v_mbcnt_lo_u32_b32 v232, -1, 0
	v_mbcnt_hi_u32_b32 v232, -1, v232
	v_lshlrev_b32_e32 v232, 7, v232
	s_waitcnt lgkmcnt(0)
	s_add_u32 s0, s0, s84
	s_addc_u32 s1, s1, 0
	global_load_dword v234, v232, s[0:1]
